# attention main loops: merged same-burst LDS waits, loop-invariant LDS address computations hoisted to the preheaders
# speedup vs baseline: 1.0011x; 1.0006x over previous
; #define AT_LOADK(t_) do { const size_t kb_ = (size_t)(t_) * 64; rk0 = *(const u32x4*)(Kh + (kb_ + kkey0) * 96 + kpart0 * 8); if (tid < 256) rk1 = *(const u32x4*)(Kh + (kb_ + kkey1) * 96 + kpart1 * 8); } while (0)
; #define AT_LOADV(t_) do { rv = *(const u32x4*)(Vh + (size_t)vdv * S + (size_t)(t_) * 64 + vpart * 8); } while (0)
; #define AT_WRITEK(t_) do { LAS unsigned char* Ks_ = lds + ((t_) & 1) * AT_KT; *(LAS u32x4*)(Ks_ + kkey0 * AT_KROW + kpart0 * 16) = rk0; if (tid < 256) *(LAS u32x4*)(Ks_ + kkey1 * AT_KROW + kpart1 * 16) = rk1; } while (0)
; DI void attn_unit(int wv, int h, int qb, const bf16_t* QB, const bf16_t* KB, const bf16_t* VT, bf16_t* MIX, LAS unsigned char* lds) {
;     ...
;     f32x16 pA0, pA1, pB0 = {}, pB1 = {}; float mA = 0.f, mB = 0.f;
;     AT_LOADK(0); AT_WRITEK(0);
;     __syncthreads();
;     AT_LOADK(1); AT_LOADV(0);
;     AT_QK(pA0, pA1, 0);
;     int t = 0;
.LBB0_799:
	s_or_b64 exec, exec, s[0:1]
	v_mad_u32_u24 v2, v22, s37, 0
	v_add_u32_e32 v201, v2, v0
	ds_read_b128 v[2:5], v201
	ds_read_b128 v[12:15], v201 offset:32
	s_lshl_b64 s[40:41], s[88:89], 21
	v_readlane_b32 s0, v240, 7
	v_ashrrev_i32_e32 v38, 3, v9
	s_waitcnt lgkmcnt(1)
	v_mfma_f32_32x32x16_bf16 v[50:65], v[2:5], v[114:117], 0
	ds_read_b128 v[2:5], v201 offset:6656
	ds_read_b128 v[26:29], v201 offset:6688
	s_add_u32 s80, s0, s40
	v_ashrrev_i32_e32 v39, 31, v38
	v_readlane_b32 s0, v240, 8
	s_addc_u32 s81, s0, s41
	v_lshlrev_b64 v[40:41], 15, v[38:39]
	v_lshlrev_b32_e32 v0, 4, v8
	s_waitcnt lgkmcnt(1)
	v_mfma_f32_32x32x16_bf16 v[66:81], v[2:5], v[114:117], 0
	v_lshl_add_u64 v[2:3], s[80:81], 0, v[40:41]
	v_and_b32_e32 v158, 0x70, v0
	v_mov_b32_e32 v159, v1
	v_lshl_add_u64 v[2:3], v[2:3], 0, v[158:159]
	global_load_dwordx4 v[146:149], v[2:3], off
	ds_read_b128 v[2:5], v201 offset:64
	ds_read_b128 v[6:9], v201 offset:96
	v_mad_i64_i32 v[42:43], s[0:1], v10, s34, 0
	v_mfma_f32_32x32x16_bf16 v[50:65], v[12:15], v[118:121], v[50:65]
	ds_read_b128 v[10:13], v201 offset:6752
	s_mov_b32 s12, 0
	s_mov_b32 s13, s12
	v_add_u32_e32 v159, 0, v24
	v_mov_b64_e32 v[24:25], s[70:71]
	v_lshlrev_b32_e32 v0, 3, v178
	s_mov_b32 s14, s12
	s_waitcnt lgkmcnt(2)
	v_mfma_f32_32x32x16_bf16 v[50:65], v[2:5], v[122:125], v[50:65]
	ds_read_b128 v[2:5], v201 offset:6720
	s_mov_b32 s15, s12
	s_mov_b32 s16, s12
	s_mov_b32 s17, s12
	s_mov_b32 s18, s12
	s_mov_b32 s19, s12
	s_mov_b32 s20, s12
	v_mfma_f32_32x32x16_bf16 v[66:81], v[26:29], v[118:121], v[66:81]
	ds_read_b128 v[26:29], v201 offset:128
	ds_read_b128 v[30:33], v201 offset:6784
	ds_read_b128 v[34:37], v201 offset:160
	ds_read_b128 v[82:85], v201 offset:6816
	s_mov_b32 s21, s12
	s_mov_b32 s22, s12
	s_mov_b32 s23, s12
	s_mov_b32 s24, s12
	s_waitcnt lgkmcnt(4)
	v_mfma_f32_32x32x16_bf16 v[66:81], v[2:5], v[122:125], v[66:81]
	s_mov_b32 s25, s12
	s_mov_b32 s26, s12
	s_mov_b32 s27, s12
	v_lshl_add_u64 v[160:161], s[40:41], 0, v[40:41]
	v_or_b32_e32 v160, v160, v158
	s_lshl_b32 s29, s10, 2
	s_mov_b32 s89, 3
	v_mfma_f32_32x32x16_bf16 v[50:65], v[6:9], v[126:129], v[50:65]
	v_or_b32_e32 v156, 0x100, v160
	v_mov_b32_e32 v157, v161
	v_mov_b32_e32 v205, 0
	s_mov_b32 s90, 5
	v_mov_b32_e32 v203, 0
	v_mfma_f32_32x32x16_bf16 v[66:81], v[10:13], v[126:129], v[66:81]
	v_mov_b64_e32 v[2:3], s[12:13]
	v_mov_b64_e32 v[16:17], s[26:27]
	v_mov_b64_e32 v[4:5], s[14:15]
	v_mov_b64_e32 v[6:7], s[16:17]
	v_mov_b64_e32 v[8:9], s[18:19]
	v_mov_b64_e32 v[10:11], s[20:21]
	v_mov_b64_e32 v[12:13], s[22:23]
	s_waitcnt lgkmcnt(3)
	v_mfma_f32_32x32x16_bf16 v[50:65], v[26:29], v[130:133], v[50:65]
	v_mul_u32_u24_e32 v27, 0x88, v22
	v_mad_i64_i32 v[22:23], s[0:1], v23, s34, v[24:25]
	v_add_u32_e32 v26, 0, v0
	v_lshl_add_u64 v[150:151], v[20:21], 1, v[22:23]
	v_lshl_add_u64 v[20:21], s[70:71], 0, v[42:43]
	v_mov_b64_e32 v[14:15], s[24:25]
	s_waitcnt lgkmcnt(2)
	v_mfma_f32_32x32x16_bf16 v[66:81], v[30:33], v[130:133], v[66:81]
	v_mul_lo_u32 v0, v38, s38
	v_lshl_add_u64 v[152:153], v[18:19], 1, v[20:21]
	v_add_u32_e32 v179, v26, v27
	v_mov_b64_e32 v[32:33], v[16:17]
	v_add_u32_e32 v0, 0, v0
	v_mov_b64_e32 v[30:31], v[14:15]
	v_mov_b64_e32 v[28:29], v[12:13]
	s_waitcnt lgkmcnt(1)
	v_mfma_f32_32x32x16_bf16 v[50:65], v[34:37], v[134:137], v[50:65]
	v_mov_b64_e32 v[48:49], v[16:17]
	v_mov_b64_e32 v[26:27], v[10:11]
	v_mov_b64_e32 v[24:25], v[8:9]
	v_mov_b64_e32 v[22:23], v[6:7]
	v_mov_b64_e32 v[20:21], v[4:5]
	v_mov_b64_e32 v[18:19], v[2:3]
	v_mov_b64_e32 v[46:47], v[14:15]
	s_waitcnt lgkmcnt(0)
	v_mfma_f32_32x32x16_bf16 v[66:81], v[82:85], v[134:137], v[66:81]
	v_mov_b64_e32 v[44:45], v[12:13]
	v_mov_b64_e32 v[42:43], v[10:11]
	v_mov_b64_e32 v[40:41], v[8:9]
	v_mov_b64_e32 v[38:39], v[6:7]
	v_mov_b64_e32 v[36:37], v[4:5]
	v_mov_b64_e32 v[34:35], v[2:3]
	s_add_u32 s52, s94, 0xad71000
	s_addc_u32 s53, s95, 0
	s_add_u32 s54, s94, 0xad74000
	s_addc_u32 s55, s95, 0
	s_add_u32 s56, s94, 0xc56b000
	s_addc_u32 s57, s95, 0
	v_add3_u32 v202, v0, v158, s33
	v_add3_u32 v208, v0, v158, s4
	v_add_u32_e32 v206, 0x6800, v179
	v_add_u32_e32 v207, 0x7800, v179
	v_add_u32_e32 v209, 0x8800, v179
	v_add_u32_e32 v241, v159, v191
	s_waitcnt vmcnt(1)
	ds_write_b128 v190, v[142:145] offset:13312
	s_and_saveexec_b64 s[8:9], s[6:7]
	s_branch .LBB0_801

.LBB0_801:
	ds_write_b128 v241, v[138:141] offset:13312
	s_or_b64 exec, exec, s[8:9]
	s_waitcnt vmcnt(0)
	ds_write2_b64 v202, v[146:147], v[148:149] offset1:1
	s_waitcnt lgkmcnt(0)
	s_barrier
	global_load_dwordx4 v[142:145], v152, s[52:53]
	s_and_saveexec_b64 s[8:9], s[6:7]
	s_cbranch_execz .LBB0_804
	global_load_dwordx4 v[138:141], v150, s[52:53]

.LBB0_813:
	ds_read_b128 v[98:101], v201 offset:13312
	ds_read_b128 v[102:105], v201 offset:13344
	v_exp_f32_e32 v50, v50
	v_exp_f32_e32 v51, v51
	s_waitcnt lgkmcnt(0)
	v_mfma_f32_32x32x16_bf16 v[82:97], v[98:101], v[114:117], v[34:49]
	v_exp_f32_e32 v52, v52
	v_exp_f32_e32 v53, v53
	v_exp_f32_e32 v54, v54
	v_exp_f32_e32 v55, v55
	v_exp_f32_e32 v56, v56
	v_exp_f32_e32 v57, v57
	v_mfma_f32_32x32x16_bf16 v[82:97], v[102:105], v[118:121], v[82:97]
	ds_read_b128 v[98:101], v201 offset:13376
	ds_read_b128 v[102:105], v201 offset:13408
	v_exp_f32_e32 v58, v58
	v_exp_f32_e32 v59, v59
	v_exp_f32_e32 v60, v60
	v_exp_f32_e32 v61, v61
	v_exp_f32_e32 v62, v62
	v_exp_f32_e32 v63, v63
	s_waitcnt lgkmcnt(0)
	v_mfma_f32_32x32x16_bf16 v[82:97], v[98:101], v[122:125], v[82:97]
	v_exp_f32_e32 v64, v64
	v_exp_f32_e32 v65, v65
	v_exp_f32_e32 v66, v66
	v_exp_f32_e32 v67, v67
	v_exp_f32_e32 v68, v68
	v_exp_f32_e32 v69, v69
	v_exp_f32_e32 v70, v70
	v_mfma_f32_32x32x16_bf16 v[82:97], v[102:105], v[126:129], v[82:97]
	ds_read_b128 v[98:101], v201 offset:13440
	ds_read_b128 v[102:105], v201 offset:13472
	ds_read_b128 v[170:173], v201 offset:19968
	ds_read_b128 v[174:177], v201 offset:20000
	v_exp_f32_e32 v71, v71
	v_exp_f32_e32 v72, v72
	v_exp_f32_e32 v73, v73
	v_exp_f32_e32 v74, v74
	v_exp_f32_e32 v75, v75
	s_waitcnt lgkmcnt(2)
	v_mfma_f32_32x32x16_bf16 v[82:97], v[98:101], v[130:133], v[82:97]
	v_exp_f32_e32 v76, v76
	v_exp_f32_e32 v77, v77
	v_exp_f32_e32 v78, v78
	v_exp_f32_e32 v79, v79
	v_exp_f32_e32 v80, v80
	v_exp_f32_e32 v81, v81
	v_mfma_f32_32x32x16_bf16 v[82:97], v[102:105], v[134:137], v[82:97]
	s_waitcnt lgkmcnt(0)
	v_mfma_f32_32x32x16_bf16 v[98:113], v[170:173], v[114:117], v[34:49]
	v_mfma_f32_32x32x16_bf16 v[98:113], v[174:177], v[118:121], v[98:113]
	ds_read_b128 v[170:173], v201 offset:20032
	ds_read_b128 v[174:177], v201 offset:20064
	s_waitcnt lgkmcnt(0)
	v_mfma_f32_32x32x16_bf16 v[98:113], v[170:173], v[122:125], v[98:113]
	v_mfma_f32_32x32x16_bf16 v[98:113], v[174:177], v[126:129], v[98:113]
	ds_read_b128 v[170:173], v201 offset:20096
	ds_read_b128 v[174:177], v201 offset:20128
	ds_read2_b64 v[180:183], v206 offset0:4 offset1:6
	s_waitcnt lgkmcnt(2)
	v_mfma_f32_32x32x16_bf16 v[98:113], v[170:173], v[130:133], v[98:113]
	ds_read2_b64 v[170:173], v206 offset1:2
	s_waitcnt lgkmcnt(2)
	v_mfma_f32_32x32x16_bf16 v[98:113], v[174:177], v[134:137], v[98:113]
	v_cvt_pk_bf16_f32 v174, v50, v51
	v_cvt_pk_bf16_f32 v175, v52, v53
	v_cvt_pk_bf16_f32 v176, v54, v55
	v_cvt_pk_bf16_f32 v177, v56, v57
	s_waitcnt lgkmcnt(0)
	s_nop 0
	v_mfma_f32_32x32x16_bf16 v[2:17], v[170:173], v[174:177], v[2:17]
	ds_read2_b64 v[170:173], v207 offset0:32 offset1:34
	s_waitcnt lgkmcnt(0)
	v_mfma_f32_32x32x16_bf16 v[18:33], v[170:173], v[174:177], v[18:33]
	ds_read2_b64 v[174:177], v207 offset0:36 offset1:38
	v_cvt_pk_bf16_f32 v170, v58, v59
	v_cvt_pk_bf16_f32 v171, v60, v61
	v_cvt_pk_bf16_f32 v172, v62, v63
	v_cvt_pk_bf16_f32 v173, v64, v65
	s_nop 1
	v_mfma_f32_32x32x16_bf16 v[2:17], v[180:183], v[170:173], v[2:17]
	ds_read2_b64 v[180:183], v206 offset0:8 offset1:10
	s_waitcnt lgkmcnt(1)
	v_mfma_f32_32x32x16_bf16 v[18:33], v[174:177], v[170:173], v[18:33]
	ds_read2_b64 v[174:177], v207 offset0:40 offset1:42
	v_cvt_pk_bf16_f32 v170, v66, v67
	v_cvt_pk_bf16_f32 v171, v68, v69
	v_cvt_pk_bf16_f32 v172, v70, v71
	v_cvt_pk_bf16_f32 v173, v72, v73
	s_waitcnt lgkmcnt(1)
	s_nop 0
	v_mfma_f32_32x32x16_bf16 v[2:17], v[180:183], v[170:173], v[2:17]
	ds_read2_b64 v[180:183], v206 offset0:12 offset1:14
	s_waitcnt lgkmcnt(1)
	v_mfma_f32_32x32x16_bf16 v[18:33], v[174:177], v[170:173], v[18:33]
	ds_read2_b64 v[174:177], v207 offset0:44 offset1:46
	v_cvt_pk_bf16_f32 v170, v74, v75
	v_cvt_pk_bf16_f32 v171, v76, v77
	v_cvt_pk_bf16_f32 v172, v78, v79
	v_cvt_pk_bf16_f32 v173, v80, v81
	s_waitcnt vmcnt(1)
	ds_write_b128 v190, v[142:145]
	s_waitcnt lgkmcnt(2)
	v_mfma_f32_32x32x16_bf16 v[2:17], v[180:183], v[170:173], v[2:17]
	s_waitcnt lgkmcnt(1)
	v_mfma_f32_32x32x16_bf16 v[18:33], v[174:177], v[170:173], v[18:33]
	s_and_saveexec_b64 s[8:9], s[6:7]
	ds_write_b128 v241, v[138:141]
	s_or_b64 exec, exec, s[8:9]
	s_waitcnt vmcnt(0)
	ds_write2_b64 v208, v[146:147], v[148:149] offset1:1
	s_waitcnt lgkmcnt(0)
	s_barrier
	global_load_dwordx4 v[142:145], v152, s[54:55]
	s_and_saveexec_b64 s[8:9], s[6:7]
	s_cbranch_execz .LBB0_817
	global_load_dwordx4 v[138:141], v150, s[54:55]

.LBB0_820:
	ds_read_b128 v[66:69], v201
	ds_read_b128 v[70:73], v201 offset:32
	v_exp_f32_e32 v163, v86
	v_exp_f32_e32 v162, v87
	s_waitcnt lgkmcnt(0)
	v_mfma_f32_32x32x16_bf16 v[50:65], v[66:69], v[114:117], v[34:49]
	v_exp_f32_e32 v82, v82
	v_exp_f32_e32 v83, v83
	v_exp_f32_e32 v84, v84
	v_exp_f32_e32 v85, v85
	v_exp_f32_e32 v87, v104
	v_exp_f32_e32 v86, v105
	v_mfma_f32_32x32x16_bf16 v[50:65], v[70:73], v[118:121], v[50:65]
	ds_read_b128 v[66:69], v201 offset:64
	ds_read_b128 v[70:73], v201 offset:96
	v_exp_f32_e32 v175, v102
	v_exp_f32_e32 v174, v103
	v_cvt_pk_bf16_f32 v102, v82, v83
	v_cvt_pk_bf16_f32 v103, v84, v85
	v_cvt_pk_bf16_f32 v104, v163, v162
	v_exp_f32_e32 v177, v96
	s_waitcnt lgkmcnt(1)
	v_mfma_f32_32x32x16_bf16 v[50:65], v[66:69], v[122:125], v[50:65]
	ds_read_b128 v[66:69], v201 offset:128
	v_exp_f32_e32 v176, v97
	v_exp_f32_e32 v98, v98
	v_exp_f32_e32 v99, v99
	v_exp_f32_e32 v100, v100
	v_exp_f32_e32 v101, v101
	v_add_f32_e32 v181, v98, v82
	s_waitcnt lgkmcnt(1)
	v_mfma_f32_32x32x16_bf16 v[50:65], v[70:73], v[126:129], v[50:65]
	ds_read_b128 v[166:169], v201 offset:6656
	ds_read_b128 v[170:173], v201 offset:6688
	ds_read_b128 v[182:185], v201 offset:6720
	ds_read_b128 v[186:189], v201 offset:6752
	ds_read_b128 v[70:73], v201 offset:160
	ds_read_b128 v[210:213], v201 offset:6784
	ds_read_b128 v[214:217], v201 offset:6816
	v_add_f32_e32 v203, v99, v83
	v_add_f32_e32 v181, 0, v181
	v_add_f32_e32 v228, v100, v84
	v_add_f32_e32 v181, v203, v181
	v_add_f32_e32 v229, v101, v85
	s_waitcnt lgkmcnt(7)
	v_mfma_f32_32x32x16_bf16 v[50:65], v[66:69], v[130:133], v[50:65]
	v_add_f32_e64 v218, v174, v162
	v_add_f32_e64 v219, v175, v163
	s_add_i32 s12, s12, 2
	s_add_i32 s0, s90, 2
	s_add_i32 s1, s89, 2
	s_waitcnt lgkmcnt(2)
	v_mfma_f32_32x32x16_bf16 v[50:65], v[70:73], v[134:137], v[50:65]
	s_cmp_ge_u32 s12, s29
	v_mfma_f32_32x32x16_bf16 v[66:81], v[166:169], v[114:117], v[34:49]
	v_exp_f32_e32 v167, v88
	v_exp_f32_e32 v166, v89
	v_exp_f32_e32 v169, v90
	v_exp_f32_e32 v89, v106
	v_exp_f32_e32 v168, v91
	v_exp_f32_e32 v88, v107
	v_exp_f32_e32 v91, v108
	v_mfma_f32_32x32x16_bf16 v[66:81], v[170:173], v[118:121], v[66:81]
	v_exp_f32_e32 v90, v109
	ds_read2_b64 v[106:109], v209 offset0:64 offset1:66
	v_exp_f32_e32 v171, v92
	v_exp_f32_e32 v170, v93
	v_exp_f32_e32 v93, v110
	v_exp_f32_e32 v92, v111
	v_mfma_f32_32x32x16_bf16 v[66:81], v[182:185], v[122:125], v[66:81]
	v_cvt_pk_bf16_f32 v105, v167, v166
	v_exp_f32_e32 v173, v94
	v_exp_f32_e32 v172, v95
	v_exp_f32_e32 v95, v112
	v_exp_f32_e32 v94, v113
	ds_read2_b64 v[110:113], v209 offset0:68 offset1:70
	v_add_f32_e32 v220, v86, v166
	v_add_f32_e32 v221, v87, v167
	v_mfma_f32_32x32x16_bf16 v[66:81], v[186:189], v[126:129], v[66:81]
	v_add_f32_e32 v222, v88, v168
	v_add_f32_e32 v223, v89, v169
	v_add_f32_e32 v96, v90, v170
	v_add_f32_e32 v97, v91, v171
	v_add_f32_e32 v224, v92, v172
	v_add_f32_e32 v225, v93, v173
	v_add_f32_e32 v226, v94, v176
	v_add_f32_e32 v227, v95, v177
	s_waitcnt lgkmcnt(3)
	v_mfma_f32_32x32x16_bf16 v[66:81], v[210:213], v[130:133], v[66:81]
	v_add_u32_e32 v210, 0x9800, v179
	ds_read2_b64 v[182:185], v210 offset0:96 offset1:98
	s_nop 0
	v_cvt_pk_bf16_f32 v212, v89, v88
	s_waitcnt lgkmcnt(2)
	v_mfma_f32_32x32x16_bf16 v[2:17], v[106:109], v[102:105], v[2:17]
	v_cvt_pk_bf16_f32 v106, v169, v168
	v_cvt_pk_bf16_f32 v107, v171, v170
	v_cvt_pk_bf16_f32 v108, v173, v172
	v_cvt_pk_bf16_f32 v109, v177, v176
	s_waitcnt lgkmcnt(0)
	v_mfma_f32_32x32x16_bf16 v[18:33], v[182:185], v[102:105], v[18:33]
	ds_read2_b64 v[102:105], v210 offset0:100 offset1:102
	v_cvt_pk_bf16_f32 v184, v175, v174
	v_cvt_pk_bf16_f32 v185, v87, v86
	v_cvt_pk_bf16_f32 v182, v98, v99
	v_cvt_pk_bf16_f32 v183, v100, v101
	v_mfma_f32_32x32x16_bf16 v[2:17], v[110:113], v[106:109], v[2:17]
	ds_read2_b64 v[110:113], v209 offset0:72 offset1:74
	ds_read2_b64 v[186:189], v210 offset0:104 offset1:106
	s_waitcnt lgkmcnt(2)
	v_mfma_f32_32x32x16_bf16 v[18:33], v[102:105], v[106:109], v[18:33]
	s_waitcnt lgkmcnt(0)
	v_mfma_f32_32x32x16_bf16 v[2:17], v[110:113], v[182:185], v[2:17]
	v_add_f32_e32 v110, v228, v181
	v_add_f32_e32 v110, v229, v110
	v_add_f32_e32 v110, v219, v110
	v_add_f32_e32 v110, v218, v110
	v_add_f32_e32 v110, v221, v110
	v_add_f32_e32 v110, v220, v110
	v_add_f32_e32 v110, v223, v110
	v_mfma_f32_32x32x16_bf16 v[18:33], v[186:189], v[182:185], v[18:33]
	v_add_f32_e32 v110, v222, v110
	v_add_f32_e32 v97, v97, v110
	v_add_f32_e32 v96, v96, v97
	v_add_f32_e32 v96, v225, v96
	v_add_f32_e32 v96, v224, v96
	v_add_f32_e32 v96, v227, v96
	v_add_f32_e32 v96, v226, v96
	v_mfma_f32_32x32x16_bf16 v[66:81], v[214:217], v[134:137], v[66:81]
	v_add_f32_e32 v203, v180, v96
	v_cvt_pk_bf16_f32 v213, v91, v90
	v_cvt_pk_bf16_f32 v214, v93, v92
	v_cvt_pk_bf16_f32 v215, v95, v94
	ds_read2_b64 v[102:105], v209 offset0:76 offset1:78
	ds_read2_b64 v[106:109], v210 offset0:108 offset1:110
	s_waitcnt lgkmcnt(0)
	v_mfma_f32_32x32x16_bf16 v[2:17], v[102:105], v[212:215], v[2:17]
	v_mfma_f32_32x32x16_bf16 v[18:33], v[106:109], v[212:215], v[18:33]
	s_cbranch_scc0 .LBB0_800
	s_add_i32 s91, s29, 4
	s_mov_b64 s[8:9], -1
	s_cmp_lt_u32 s12, s91
	v_lshlrev_b32_e32 v158, 2, v178
	s_cbranch_scc1 .LBB0_823
	v_lshlrev_b32_e32 v0, 2, v178
	s_mov_b64 s[8:9], 0

; #define AT_LOADK(t_) do { const size_t kb_ = (size_t)(t_) * 64; rk0 = *(const u32x4*)(Kh + (kb_ + kkey0) * 96 + kpart0 * 8); if (tid < 256) rk1 = *(const u32x4*)(Kh + (kb_ + kkey1) * 96 + kpart1 * 8); } while (0)
; #define AT_LOADV(t_) do { rv = *(const u32x4*)(Vh + (size_t)vdv * S + (size_t)(t_) * 64 + vpart * 8); } while (0)
; #define AT_WRITEK(t_) do { LAS unsigned char* Ks_ = lds + ((t_) & 1) * AT_KT; *(LAS u32x4*)(Ks_ + kkey0 * AT_KROW + kpart0 * 16) = rk0; if (tid < 256) *(LAS u32x4*)(Ks_ + kkey1 * AT_KROW + kpart1 * 16) = rk1; } while (0)
; DI void attn_unit(int wv, int h, int qb, const bf16_t* QB, const bf16_t* KB, const bf16_t* VT, bf16_t* MIX, LAS unsigned char* lds) {
;     ...
;     f32x16 pA0, pA1, pB0 = {}, pB1 = {}; float mA = 0.f, mB = 0.f;
;     AT_LOADK(0); AT_WRITEK(0);
;     __syncthreads();
;     AT_LOADK(1); AT_LOADV(0);
;     AT_QK(pA0, pA1, 0);
;     int t = 0;
.LBB0_871:
	s_or_b64 exec, exec, s[8:9]
	v_mad_u32_u24 v3, v8, s37, 0
	v_add_u32_e32 v203, v3, v0
	ds_read_b128 v[4:7], v203
	ds_read_b128 v[12:15], v203 offset:32
	v_ashrrev_i32_e32 v20, 3, v10
	v_ashrrev_i32_e32 v21, 31, v20
	v_and_b32_e32 v0, 7, v9
	s_waitcnt lgkmcnt(1)
	v_mfma_f32_32x32x16_bf16 v[64:79], v[4:7], v[128:131], 0
	ds_read_b128 v[4:7], v203 offset:6656
	ds_read_b128 v[16:19], v203 offset:6688
	v_lshlrev_b64 v[174:175], 15, v[20:21]
	v_lshlrev_b32_e32 v168, 4, v0
	v_mov_b32_e32 v169, v1
	v_mad_i64_i32 v[176:177], s[0:1], v11, s34, 0
	v_lshlrev_b32_e32 v0, 3, v187
	s_waitcnt lgkmcnt(2)
	v_mfma_f32_32x32x16_bf16 v[64:79], v[12:15], v[132:135], v[64:79]
	s_lshl_b32 s15, s5, 2
	v_add_u32_e32 v204, 0, v0
	v_mul_lo_u32 v0, v20, s38
	s_mov_b32 s76, 0
	s_cmp_eq_u32 s5, 0
	v_mul_u32_u24_e32 v205, 0x88, v8
	v_add_u32_e32 v206, 0, v2
	s_waitcnt lgkmcnt(1)
	v_mfma_f32_32x32x16_bf16 v[80:95], v[4:7], v[128:131], 0
	ds_read_b128 v[4:7], v203 offset:64
	ds_read_b128 v[12:15], v203 offset:96
	v_add_u32_e32 v207, 0, v0
	s_waitcnt lgkmcnt(1)
	v_mfma_f32_32x32x16_bf16 v[64:79], v[4:7], v[136:139], v[64:79]
	ds_read_b128 v[4:7], v203 offset:6720
	v_mfma_f32_32x32x16_bf16 v[80:95], v[16:19], v[132:135], v[80:95]
	ds_read_b128 v[16:19], v203 offset:6752
	s_waitcnt lgkmcnt(1)
	v_mfma_f32_32x32x16_bf16 v[80:95], v[4:7], v[136:139], v[80:95]
	v_lshl_add_u64 v[4:5], s[80:81], 0, v[174:175]
	v_lshl_add_u64 v[4:5], v[4:5], 0, v[168:169]
	global_load_dwordx4 v[160:163], v[4:5], off
	ds_read_b128 v[4:7], v203 offset:128
	v_mfma_f32_32x32x16_bf16 v[64:79], v[12:15], v[140:143], v[64:79]
	s_waitcnt lgkmcnt(1)
	v_mfma_f32_32x32x16_bf16 v[80:95], v[16:19], v[140:143], v[80:95]
	ds_read_b128 v[10:13], v203 offset:6784
	ds_read_b128 v[14:17], v203 offset:160
	s_waitcnt lgkmcnt(2)
	v_mfma_f32_32x32x16_bf16 v[64:79], v[4:7], v[144:147], v[64:79]
	ds_read_b128 v[4:7], v203 offset:6816
	s_waitcnt lgkmcnt(2)
	v_mfma_f32_32x32x16_bf16 v[80:95], v[10:13], v[144:147], v[80:95]
	s_waitcnt lgkmcnt(1)
	v_mfma_f32_32x32x16_bf16 v[64:79], v[14:17], v[148:151], v[64:79]
	s_waitcnt lgkmcnt(0)
	v_mfma_f32_32x32x16_bf16 v[80:95], v[4:7], v[148:151], v[80:95]
	s_cbranch_scc1 .LBB0_895
	v_mov_b64_e32 v[2:3], s[70:71]
	v_mad_i64_i32 v[2:3], s[0:1], v186, s34, v[2:3]
	v_lshl_add_u64 v[178:179], v[172:173], 1, v[2:3]
	v_lshl_add_u64 v[2:3], s[70:71], 0, v[176:177]
	v_lshl_add_u64 v[180:181], v[170:171], 1, v[2:3]
	v_lshl_add_u64 v[2:3], s[40:41], 0, v[174:175]
	v_mov_b32_e32 v14, v1
	v_mov_b32_e32 v15, v1
	v_lshl_add_u64 v[182:183], v[2:3], 0, v[168:169]
	v_mov_b32_e32 v0, v1
	v_mov_b32_e32 v2, v1
	v_mov_b32_e32 v3, v1
	v_mov_b32_e32 v4, v1
	v_mov_b32_e32 v5, v1
	v_mov_b32_e32 v6, v1
	v_mov_b32_e32 v7, v1
	v_mov_b32_e32 v8, v1
	v_mov_b32_e32 v9, v1
	v_mov_b32_e32 v10, v1
	v_mov_b32_e32 v11, v1
	v_mov_b32_e32 v12, v1
	v_mov_b32_e32 v13, v1
	v_mov_b64_e32 v[46:47], v[14:15]
	v_mov_b64_e32 v[30:31], v[14:15]
	v_mov_b64_e32 v[62:63], v[14:15]
	v_readlane_b32 s88, v240, 15
	v_mov_b32_e32 v210, 0
	v_add_u32_e32 v169, v206, v202
	v_mov_b64_e32 v[44:45], v[12:13]
	v_mov_b64_e32 v[42:43], v[10:11]
	v_mov_b64_e32 v[40:41], v[8:9]
	v_mov_b64_e32 v[38:39], v[6:7]
	v_mov_b64_e32 v[36:37], v[4:5]
	v_mov_b64_e32 v[34:35], v[2:3]
	v_mov_b64_e32 v[32:33], v[0:1]
	v_mov_b64_e32 v[28:29], v[12:13]
	v_mov_b64_e32 v[26:27], v[10:11]
	v_mov_b64_e32 v[24:25], v[8:9]
	v_mov_b64_e32 v[22:23], v[6:7]
	v_mov_b64_e32 v[20:21], v[4:5]
	v_mov_b64_e32 v[18:19], v[2:3]
	v_mov_b64_e32 v[16:17], v[0:1]
	v_mov_b64_e32 v[60:61], v[12:13]
	v_mov_b64_e32 v[58:59], v[10:11]
	v_mov_b64_e32 v[56:57], v[8:9]
	v_mov_b64_e32 v[54:55], v[6:7]
	v_mov_b64_e32 v[52:53], v[4:5]
	v_mov_b64_e32 v[50:51], v[2:3]
	v_mov_b64_e32 v[48:49], v[0:1]
	v_mov_b32_e32 v208, 0
	v_readlane_b32 s89, v240, 16
	v_add3_u32 v242, v207, v168, s33
	v_add3_u32 v243, v207, v168, s4
	v_add_u32_e32 v244, v204, v205
	v_add_u32_e32 v245, 0x7800, v244
	v_add_u32_e32 v246, 0x8800, v244
	v_add_u32_e32 v247, 0x9800, v244
	v_add_u32_e32 v244, 0x6800, v244
	s_add_u32 s52, s94, 0xad71000
	s_addc_u32 s53, s95, 0
	s_add_u32 s54, s94, 0xad74000
	s_addc_u32 s55, s95, 0
	s_add_u32 s56, s94, 0xc56b000
	s_addc_u32 s57, s95, 0
	s_branch .LBB0_876

.LBB0_875:
	ds_read_b128 v[2:5], v203
	ds_read_b128 v[6:9], v203 offset:32
	v_exp_f32_e32 v11, v100
	v_exp_f32_e32 v10, v101
	v_exp_f32_e32 v96, v96
	s_waitcnt lgkmcnt(0)
	v_mfma_f32_32x32x16_bf16 v[64:79], v[2:5], v[128:131], v[48:63]
	v_exp_f32_e32 v97, v97
	v_exp_f32_e32 v98, v98
	v_exp_f32_e32 v99, v99
	v_exp_f32_e32 v185, v126
	v_exp_f32_e32 v184, v127
	v_cvt_pk_bf16_f32 v100, v96, v97
	v_cvt_pk_bf16_f32 v101, v98, v99
	v_mfma_f32_32x32x16_bf16 v[64:79], v[6:9], v[132:135], v[64:79]
	ds_read_b128 v[2:5], v203 offset:64
	ds_read_b128 v[6:9], v203 offset:96
	v_exp_f32_e32 v112, v112
	v_exp_f32_e32 v113, v113
	v_exp_f32_e32 v114, v114
	v_exp_f32_e32 v115, v115
	v_add_f32_e32 v189, v112, v96
	v_add_f32_e32 v208, v113, v97
	s_waitcnt lgkmcnt(1)
	v_mfma_f32_32x32x16_bf16 v[64:79], v[2:5], v[136:139], v[64:79]
	ds_read_b128 v[2:5], v203 offset:128
	v_add_f32_e32 v211, v114, v98
	v_add_f32_e32 v236, v115, v99
	s_add_i32 s76, s76, 2
	s_waitcnt lgkmcnt(1)
	v_mfma_f32_32x32x16_bf16 v[64:79], v[6:9], v[140:143], v[64:79]
	ds_read_b128 v[6:9], v203 offset:160
	s_cmp_ge_u32 s76, s15
	s_waitcnt lgkmcnt(1)
	v_mfma_f32_32x32x16_bf16 v[64:79], v[2:5], v[144:147], v[64:79]
	ds_read_b128 v[2:5], v203 offset:6656
	ds_read_b128 v[12:15], v203 offset:6688
	ds_read_b128 v[212:215], v203 offset:6720
	ds_read_b128 v[216:219], v203 offset:6752
	ds_read_b128 v[220:223], v203 offset:6784
	ds_read_b128 v[224:227], v203 offset:6816
	s_waitcnt lgkmcnt(4)
	v_mfma_f32_32x32x16_bf16 v[80:95], v[2:5], v[128:131], v[48:63]
	v_exp_f32_e32 v3, v116
	v_exp_f32_e32 v2, v117
	v_exp_f32_e32 v5, v118
	v_exp_f32_e32 v4, v119
	v_exp_f32_e32 v117, v104
	v_exp_f32_e32 v116, v105
	v_exp_f32_e32 v119, v106
	v_mfma_f32_32x32x16_bf16 v[80:95], v[12:15], v[132:135], v[80:95]
	v_exp_f32_e32 v15, v102
	v_exp_f32_e32 v14, v103
	v_exp_f32_e32 v118, v107
	v_cvt_pk_bf16_f32 v102, v11, v10
	v_exp_f32_e32 v13, v124
	v_exp_f32_e32 v12, v125
	s_waitcnt lgkmcnt(2)
	v_mfma_f32_32x32x16_bf16 v[80:95], v[212:215], v[136:139], v[80:95]
	v_cvt_pk_bf16_f32 v124, v117, v116
	v_cvt_pk_bf16_f32 v125, v119, v118
	v_add_f32_e32 v190, v2, v10
	v_add_f32_e32 v191, v3, v11
	v_add_f32_e32 v228, v4, v14
	v_add_f32_e32 v229, v5, v15
	v_mfma_f32_32x32x16_bf16 v[80:95], v[216:219], v[140:143], v[80:95]
	v_mfma_f32_32x32x16_bf16 v[64:79], v[6:9], v[148:151], v[64:79]
	v_exp_f32_e32 v7, v120
	v_exp_f32_e32 v6, v121
	v_exp_f32_e32 v121, v108
	v_exp_f32_e32 v120, v109
	v_exp_f32_e32 v9, v122
	v_exp_f32_e32 v8, v123
	s_waitcnt lgkmcnt(1)
	v_mfma_f32_32x32x16_bf16 v[80:95], v[220:223], v[144:147], v[80:95]
	v_exp_f32_e32 v123, v110
	v_exp_f32_e32 v122, v111
	ds_read2_b64 v[104:107], v246 offset0:64 offset1:66
	v_cvt_pk_bf16_f32 v103, v15, v14
	ds_read2_b64 v[108:111], v247 offset0:96 offset1:98
	s_waitcnt lgkmcnt(1)
	v_mfma_f32_32x32x16_bf16 v[32:47], v[104:107], v[100:103], v[32:47]
	ds_read2_b64 v[104:107], v246 offset0:68 offset1:70
	v_cvt_pk_bf16_f32 v126, v121, v120
	v_add_f32_e32 v230, v6, v116
	v_add_f32_e32 v231, v7, v117
	v_cvt_pk_bf16_f32 v216, v7, v6
	v_add_f32_e32 v232, v8, v118
	v_add_f32_e32 v233, v9, v119
	v_add_f32_e32 v234, v12, v120
	v_add_f32_e32 v235, v13, v121
	s_waitcnt lgkmcnt(1)
	v_mfma_f32_32x32x16_bf16 v[16:31], v[108:111], v[100:103], v[16:31]
	v_cvt_pk_bf16_f32 v127, v123, v122
	ds_read2_b64 v[100:103], v247 offset0:100 offset1:102
	v_cvt_pk_bf16_f32 v110, v3, v2
	v_cvt_pk_bf16_f32 v108, v112, v113
	v_cvt_pk_bf16_f32 v109, v114, v115
	s_waitcnt lgkmcnt(1)
	v_mfma_f32_32x32x16_bf16 v[32:47], v[104:107], v[124:127], v[32:47]
	v_add_f32_e32 v220, v184, v122
	v_add_f32_e32 v221, v185, v123
	v_cvt_pk_bf16_f32 v111, v5, v4
	ds_read2_b64 v[104:107], v246 offset0:72 offset1:74
	ds_read2_b64 v[212:215], v247 offset0:104 offset1:106
	s_waitcnt lgkmcnt(2)
	v_mfma_f32_32x32x16_bf16 v[16:31], v[100:103], v[124:127], v[16:31]
	s_nop 0
	v_cvt_pk_bf16_f32 v217, v9, v8
	s_nop 0
	v_cvt_pk_bf16_f32 v218, v13, v12
	s_waitcnt lgkmcnt(1)
	v_mfma_f32_32x32x16_bf16 v[32:47], v[104:107], v[108:111], v[32:47]
	v_cvt_pk_bf16_f32 v219, v185, v184
	ds_read2_b64 v[100:103], v246 offset0:76 offset1:78
	ds_read2_b64 v[104:107], v247 offset0:108 offset1:110
	v_add_f32_e32 v0, 0, v189
	v_add_f32_e32 v0, v208, v0
	v_add_f32_e32 v0, v211, v0
	v_add_f32_e32 v0, v236, v0
	s_waitcnt lgkmcnt(2)
	v_mfma_f32_32x32x16_bf16 v[16:31], v[212:215], v[108:111], v[16:31]
	v_add_f32_e32 v0, v191, v0
	v_add_f32_e32 v0, v190, v0
	v_add_f32_e32 v0, v229, v0
	v_add_f32_e32 v0, v228, v0
	v_add_f32_e32 v0, v231, v0
	v_add_f32_e32 v0, v230, v0
	v_add_f32_e32 v0, v233, v0
	v_mfma_f32_32x32x16_bf16 v[80:95], v[224:227], v[148:151], v[80:95]
	v_add_f32_e32 v0, v232, v0
	v_add_f32_e32 v0, v235, v0
	v_add_f32_e32 v0, v234, v0
	v_add_f32_e32 v0, v221, v0
	v_add_f32_e32 v0, v220, v0
	v_add_f32_e32 v208, v188, v0
	s_waitcnt lgkmcnt(0)
	v_mfma_f32_32x32x16_bf16 v[32:47], v[100:103], v[216:219], v[32:47]
	v_mfma_f32_32x32x16_bf16 v[16:31], v[104:107], v[216:219], v[16:31]
	s_cbranch_scc1 .LBB0_894
.LBB0_876:
	s_waitcnt vmcnt(1)
	ds_write_b128 v201, v[156:159] offset:13312
	s_and_saveexec_b64 s[8:9], s[6:7]
	ds_write_b128 v169, v[152:155] offset:13312
	s_or_b64 exec, exec, s[8:9]
	s_waitcnt vmcnt(0)
	ds_write2_b64 v242, v[160:161], v[162:163] offset1:1
	s_waitcnt lgkmcnt(0)
	s_barrier
	global_load_dwordx4 v[2:5], v180, s[52:53]
	s_and_saveexec_b64 s[8:9], s[6:7]
	s_cbranch_execz .LBB0_880
	global_load_dwordx4 v[152:155], v178, s[52:53]

.LBB0_889:
	ds_read_b128 v[112:115], v203 offset:13312
	ds_read_b128 v[116:119], v203 offset:13344
	v_exp_f32_e32 v64, v64
	s_waitcnt lgkmcnt(0)
	v_mfma_f32_32x32x16_bf16 v[96:111], v[112:115], v[128:131], v[48:63]
	v_exp_f32_e32 v65, v65
	v_exp_f32_e32 v66, v66
	v_exp_f32_e32 v67, v67
	v_exp_f32_e32 v68, v68
	v_exp_f32_e32 v69, v69
	v_exp_f32_e32 v70, v70
	v_exp_f32_e32 v71, v71
	v_mfma_f32_32x32x16_bf16 v[96:111], v[116:119], v[132:135], v[96:111]
	ds_read_b128 v[112:115], v203 offset:13376
	ds_read_b128 v[116:119], v203 offset:13408
	v_exp_f32_e32 v72, v72
	v_exp_f32_e32 v73, v73
	v_exp_f32_e32 v74, v74
	v_exp_f32_e32 v75, v75
	v_exp_f32_e32 v76, v76
	s_waitcnt lgkmcnt(0)
	v_mfma_f32_32x32x16_bf16 v[96:111], v[112:115], v[136:139], v[96:111]
	v_exp_f32_e32 v77, v77
	v_exp_f32_e32 v78, v78
	v_exp_f32_e32 v79, v79
	v_exp_f32_e32 v80, v80
	v_exp_f32_e32 v81, v81
	v_exp_f32_e32 v82, v82
	v_exp_f32_e32 v83, v83
	v_mfma_f32_32x32x16_bf16 v[96:111], v[116:119], v[140:143], v[96:111]
	ds_read_b128 v[112:115], v203 offset:13440
	ds_read_b128 v[116:119], v203 offset:13472
	ds_read_b128 v[156:159], v203 offset:19968
	ds_read_b128 v[160:163], v203 offset:20000
	v_exp_f32_e32 v84, v84
	v_exp_f32_e32 v85, v85
	v_exp_f32_e32 v86, v86
	v_exp_f32_e32 v87, v87
	v_exp_f32_e32 v88, v88
	s_waitcnt lgkmcnt(2)
	v_mfma_f32_32x32x16_bf16 v[96:111], v[112:115], v[144:147], v[96:111]
	v_exp_f32_e32 v89, v89
	v_exp_f32_e32 v90, v90
	v_exp_f32_e32 v91, v91
	v_exp_f32_e32 v92, v92
	v_exp_f32_e32 v93, v93
	v_exp_f32_e32 v94, v94
	v_exp_f32_e32 v95, v95
	v_mfma_f32_32x32x16_bf16 v[96:111], v[116:119], v[148:151], v[96:111]
	s_waitcnt lgkmcnt(0)
	v_mfma_f32_32x32x16_bf16 v[112:127], v[156:159], v[128:131], v[48:63]
	v_mfma_f32_32x32x16_bf16 v[112:127], v[160:163], v[132:135], v[112:127]
	ds_read_b128 v[156:159], v203 offset:20032
	ds_read_b128 v[160:163], v203 offset:20064
	s_waitcnt lgkmcnt(0)
	v_mfma_f32_32x32x16_bf16 v[112:127], v[156:159], v[136:139], v[112:127]
	v_mfma_f32_32x32x16_bf16 v[112:127], v[160:163], v[140:143], v[112:127]
	ds_read_b128 v[156:159], v203 offset:20096
	ds_read_b128 v[160:163], v203 offset:20128
	ds_read2_b64 v[188:191], v244 offset0:4 offset1:6
	s_waitcnt lgkmcnt(2)
	v_mfma_f32_32x32x16_bf16 v[112:127], v[156:159], v[144:147], v[112:127]
	ds_read2_b64 v[156:159], v244 offset1:2
	s_waitcnt lgkmcnt(2)
	v_mfma_f32_32x32x16_bf16 v[112:127], v[160:163], v[148:151], v[112:127]
	v_cvt_pk_bf16_f32 v160, v64, v65
	v_cvt_pk_bf16_f32 v161, v66, v67
	v_cvt_pk_bf16_f32 v162, v68, v69
	v_cvt_pk_bf16_f32 v163, v70, v71
	s_waitcnt lgkmcnt(0)
	s_nop 0
	v_mfma_f32_32x32x16_bf16 v[32:47], v[156:159], v[160:163], v[32:47]
	ds_read2_b64 v[156:159], v245 offset0:32 offset1:34
	s_waitcnt lgkmcnt(0)
	v_mfma_f32_32x32x16_bf16 v[16:31], v[156:159], v[160:163], v[16:31]
	ds_read2_b64 v[160:163], v245 offset0:36 offset1:38
	v_cvt_pk_bf16_f32 v156, v72, v73
	v_cvt_pk_bf16_f32 v157, v74, v75
	v_cvt_pk_bf16_f32 v158, v76, v77
	v_cvt_pk_bf16_f32 v159, v78, v79
	s_nop 1
	v_mfma_f32_32x32x16_bf16 v[32:47], v[188:191], v[156:159], v[32:47]
	ds_read2_b64 v[188:191], v244 offset0:8 offset1:10
	s_waitcnt lgkmcnt(1)
	v_mfma_f32_32x32x16_bf16 v[16:31], v[160:163], v[156:159], v[16:31]
	ds_read2_b64 v[160:163], v245 offset0:40 offset1:42
	v_cvt_pk_bf16_f32 v156, v80, v81
	v_cvt_pk_bf16_f32 v157, v82, v83
	v_cvt_pk_bf16_f32 v158, v84, v85
	v_cvt_pk_bf16_f32 v159, v86, v87
	s_waitcnt lgkmcnt(1)
	s_nop 0
	v_mfma_f32_32x32x16_bf16 v[32:47], v[188:191], v[156:159], v[32:47]
	ds_read2_b64 v[188:191], v244 offset0:12 offset1:14
	s_waitcnt lgkmcnt(1)
	v_mfma_f32_32x32x16_bf16 v[16:31], v[160:163], v[156:159], v[16:31]
	ds_read2_b64 v[160:163], v245 offset0:44 offset1:46
	v_cvt_pk_bf16_f32 v156, v88, v89
	v_cvt_pk_bf16_f32 v157, v90, v91
	v_cvt_pk_bf16_f32 v158, v92, v93
	v_cvt_pk_bf16_f32 v159, v94, v95
	s_waitcnt vmcnt(1)
	ds_write_b128 v201, v[2:5]
	s_waitcnt lgkmcnt(2)
	v_mfma_f32_32x32x16_bf16 v[32:47], v[188:191], v[156:159], v[32:47]
	s_waitcnt lgkmcnt(1)
	v_mfma_f32_32x32x16_bf16 v[16:31], v[160:163], v[156:159], v[16:31]
	s_and_saveexec_b64 s[8:9], s[6:7]
	ds_write_b128 v169, v[152:155]
	s_or_b64 exec, exec, s[8:9]
	s_waitcnt vmcnt(0)
	ds_write2_b64 v243, v[6:7], v[8:9] offset1:1
	s_waitcnt lgkmcnt(0)
	s_barrier
	global_load_dwordx4 v[156:159], v180, s[54:55]
	s_and_saveexec_b64 s[8:9], s[6:7]
	s_cbranch_execz .LBB0_873
	global_load_dwordx4 v[152:155], v178, s[54:55]
	s_branch .LBB0_873
